# attention PV block: four pairs of adjacent scalar row-sum adds packed into v_pk_add_f32 (4 fewer VALU per key tile), on top of the mega bundle
# baseline (speedup 1.0000x reference)
.LBB0_1051:
	v_pk_add_f32 v[208:209], v[64:65], v[166:167] op_sel:[0,1] op_sel_hi:[1,1] neg_lo:[0,1] neg_hi:[0,1]
	v_pk_add_f32 v[210:211], v[66:67], v[166:167] op_sel:[0,1] op_sel_hi:[1,1] neg_lo:[0,1] neg_hi:[0,1]
	v_pk_add_f32 v[212:213], v[68:69], v[166:167] op_sel:[0,1] op_sel_hi:[1,1] neg_lo:[0,1] neg_hi:[0,1]
	v_pk_add_f32 v[214:215], v[70:71], v[166:167] op_sel:[0,1] op_sel_hi:[1,1] neg_lo:[0,1] neg_hi:[0,1]
	v_pk_add_f32 v[216:217], v[72:73], v[166:167] op_sel:[0,1] op_sel_hi:[1,1] neg_lo:[0,1] neg_hi:[0,1]
	v_pk_add_f32 v[218:219], v[74:75], v[166:167] op_sel:[0,1] op_sel_hi:[1,1] neg_lo:[0,1] neg_hi:[0,1]
	v_pk_add_f32 v[220:221], v[76:77], v[166:167] op_sel:[0,1] op_sel_hi:[1,1] neg_lo:[0,1] neg_hi:[0,1]
	v_pk_add_f32 v[222:223], v[78:79], v[166:167] op_sel:[0,1] op_sel_hi:[1,1] neg_lo:[0,1] neg_hi:[0,1]
	v_lshl_add_u32 v191, v179, 1, s26
	v_add3_u32 v198, v191, v158, v178
	v_add_u32_e32 v199, 0x3000, v198
	v_exp_f32_e32 v190, v208
	ds_read2_b64 v[64:67], v199 offset0:128 offset1:130
	v_exp_f32_e32 v191, v209
	v_exp_f32_e32 v192, v210
	v_exp_f32_e32 v193, v211
	v_exp_f32_e32 v194, v212
	v_cvt_pk_bf16_f32 v70, v92, v93
	v_exp_f32_e32 v195, v213
	v_exp_f32_e32 v92, v214
	v_exp_f32_e32 v93, v215
	v_cvt_pk_bf16_f32 v68, v88, v89
	v_cvt_pk_bf16_f32 v69, v90, v91
	v_cvt_pk_bf16_f32 v71, v94, v95
	v_cvt_pk_bf16_f32 v88, v190, v191
	v_cvt_pk_bf16_f32 v89, v192, v193
	v_cvt_pk_bf16_f32 v90, v194, v195
	v_cvt_pk_bf16_f32 v91, v92, v93
	v_add_u32_e32 v198, 0x4000, v198
	s_waitcnt lgkmcnt(0)
	v_mfma_f32_32x32x16_bf16 v[48:63], v[64:67], v[68:71], v[48:63]
	v_exp_f32_e32 v196, v218
	v_mfma_f32_32x32x16_bf16 v[16:31], v[64:67], v[88:91], v[16:31]
	ds_read2_b64 v[64:67], v198 offset0:160 offset1:162
	v_exp_f32_e32 v197, v219
	v_exp_f32_e32 v74, v220
	v_exp_f32_e32 v75, v221
	s_waitcnt lgkmcnt(0)
	v_mfma_f32_32x32x16_bf16 v[32:47], v[64:67], v[68:71], v[32:47]
	v_exp_f32_e32 v94, v216
	v_exp_f32_e32 v95, v217
	ds_read2_b64 v[68:71], v199 offset0:132 offset1:134
	v_cvt_pk_bf16_f32 v73, v196, v197
	v_cvt_pk_bf16_f32 v72, v94, v95
	v_mfma_f32_32x32x16_bf16 v[0:15], v[64:67], v[88:91], v[0:15]
	v_exp_f32_e32 v88, v222
	v_exp_f32_e32 v89, v223
	ds_read2_b64 v[76:79], v198 offset0:164 offset1:166
	v_cvt_pk_bf16_f32 v64, v80, v81
	v_cvt_pk_bf16_f32 v65, v82, v83
	v_cvt_pk_bf16_f32 v66, v84, v85
	v_cvt_pk_bf16_f32 v67, v86, v87
	v_pk_add_f32 v[80:81], v[194:195], v[74:75]
	v_cvt_pk_bf16_f32 v74, v74, v75
	v_cvt_pk_bf16_f32 v75, v88, v89
	s_waitcnt lgkmcnt(1)
	v_mfma_f32_32x32x16_bf16 v[48:63], v[68:71], v[64:67], v[48:63]
	v_pk_add_f32 v[82:83], v[192:193], v[196:197]
	v_mfma_f32_32x32x16_bf16 v[16:31], v[68:71], v[72:75], v[16:31]
	v_pk_add_f32 v[68:69], v[190:191], v[94:95]
	v_pk_add_f32 v[70:71], v[92:93], v[88:89]
	v_pk_add_f32 v[68:69], v[68:69], v[80:81]
	v_pk_add_f32 v[70:71], v[82:83], v[70:71]
	s_nop 0
	v_pk_add_f32 v[68:69], v[68:69], v[70:71]
	s_nop 0
	v_add_f32_e32 v68, v68, v69
	s_waitcnt lgkmcnt(0)
	v_mfma_f32_32x32x16_bf16 v[32:47], v[76:79], v[64:67], v[32:47]
	v_mov_b32_e32 v64, v68
	s_nop 1
	v_permlane32_swap_b32_e32 v64, v68
	v_add_f32_e32 v65, v188, v189
	v_add_f32_e32 v162, v162, v65
	s_waitcnt lgkmcnt(0)
	v_add_f32_e32 v64, v68, v64
	v_add_f32_e32 v160, v160, v64
	v_mfma_f32_32x32x16_bf16 v[0:15], v[76:79], v[72:75], v[0:15]
